# P0 phase_mod k-loop: fully unrolled rolling window of 20 weight-row loads in flight (was 8 per batch with full drain); same fma order
# speedup vs baseline: 1.0018x; 1.0018x over previous
.LBB0_959:
	s_mul_hi_i32 s0, s3, 0x2aaaaaab
	s_lshr_b32 s1, s0, 31
	s_ashr_i32 s4, s0, 3
	s_add_i32 s4, s4, s1
	s_mul_i32 s0, s4, 48
	s_sub_i32 s0, s3, s0
	s_lshl_b32 s0, s0, 7
	s_ashr_i32 s1, s0, 31
	s_mul_i32 s6, s4, 0x1800000
	s_lshl_b64 s[0:1], s[0:1], 2
	s_mul_hi_i32 s5, s4, 0x1800000
	s_add_u32 s6, s6, s0
	s_addc_u32 s7, s5, s1
	s_waitcnt vmcnt(0)
	v_mov_b32_e32 v26, 0
	v_lshl_add_u64 v[44:45], v[42:43], 0, s[6:7]
	s_mov_b64 s[6:7], 0
	v_mov_b32_e32 v46, v39
	v_mov_b32_e32 v27, v26
	v_mov_b32_e32 v28, v26
	v_mov_b32_e32 v29, v26
	v_mov_b32_e32 v30, v26
	v_mov_b32_e32 v31, v26
	v_mov_b32_e32 v32, v26
	v_mov_b32_e32 v33, v26
	v_mov_b32_e32 v34, v26
	v_mov_b32_e32 v35, v26
	v_mov_b32_e32 v36, v26
	v_mov_b32_e32 v37, v26
	s_mov_b64 s[40:41], 0x6000
	v_mov_b64_e32 v[180:181], v[44:45]
	ds_read_b128 v[2:5], v46
	ds_read_b128 v[6:9], v46 offset:16
	ds_read_b128 v[10:13], v46 offset:4096
	ds_read_b128 v[14:17], v46 offset:4112
	ds_read_b128 v[18:21], v46 offset:8192
	ds_read_b128 v[22:25], v46 offset:8208
	global_load_dwordx4 v[100:103], v[180:181], off
	v_lshl_add_u64 v[180:181], s[40:41], 0, v[180:181]
	global_load_dwordx4 v[104:107], v[180:181], off
	v_lshl_add_u64 v[180:181], s[40:41], 0, v[180:181]
	global_load_dwordx4 v[108:111], v[180:181], off
	v_lshl_add_u64 v[180:181], s[40:41], 0, v[180:181]
	global_load_dwordx4 v[112:115], v[180:181], off
	v_lshl_add_u64 v[180:181], s[40:41], 0, v[180:181]
	global_load_dwordx4 v[116:119], v[180:181], off
	v_lshl_add_u64 v[180:181], s[40:41], 0, v[180:181]
	global_load_dwordx4 v[120:123], v[180:181], off
	v_lshl_add_u64 v[180:181], s[40:41], 0, v[180:181]
	global_load_dwordx4 v[124:127], v[180:181], off
	v_lshl_add_u64 v[180:181], s[40:41], 0, v[180:181]
	global_load_dwordx4 v[128:131], v[180:181], off
	v_lshl_add_u64 v[180:181], s[40:41], 0, v[180:181]
	global_load_dwordx4 v[132:135], v[180:181], off
	v_lshl_add_u64 v[180:181], s[40:41], 0, v[180:181]
	global_load_dwordx4 v[136:139], v[180:181], off
	v_lshl_add_u64 v[180:181], s[40:41], 0, v[180:181]
	global_load_dwordx4 v[140:143], v[180:181], off
	v_lshl_add_u64 v[180:181], s[40:41], 0, v[180:181]
	global_load_dwordx4 v[144:147], v[180:181], off
	v_lshl_add_u64 v[180:181], s[40:41], 0, v[180:181]
	global_load_dwordx4 v[148:151], v[180:181], off
	v_lshl_add_u64 v[180:181], s[40:41], 0, v[180:181]
	global_load_dwordx4 v[152:155], v[180:181], off
	v_lshl_add_u64 v[180:181], s[40:41], 0, v[180:181]
	global_load_dwordx4 v[156:159], v[180:181], off
	v_lshl_add_u64 v[180:181], s[40:41], 0, v[180:181]
	global_load_dwordx4 v[160:163], v[180:181], off
	v_lshl_add_u64 v[180:181], s[40:41], 0, v[180:181]
	global_load_dwordx4 v[164:167], v[180:181], off
	v_lshl_add_u64 v[180:181], s[40:41], 0, v[180:181]
	global_load_dwordx4 v[168:171], v[180:181], off
	v_lshl_add_u64 v[180:181], s[40:41], 0, v[180:181]
	global_load_dwordx4 v[172:175], v[180:181], off
	v_lshl_add_u64 v[180:181], s[40:41], 0, v[180:181]
	global_load_dwordx4 v[176:179], v[180:181], off
	v_lshl_add_u64 v[180:181], s[40:41], 0, v[180:181]
	ds_read_b128 v[50:53], v46 offset:32
	ds_read_b128 v[54:57], v46 offset:48
	ds_read_b128 v[58:61], v46 offset:4128
	ds_read_b128 v[62:65], v46 offset:4144
	ds_read_b128 v[66:69], v46 offset:8224
	ds_read_b128 v[70:73], v46 offset:8240
	s_waitcnt lgkmcnt(6)
	s_waitcnt vmcnt(19)
	v_pk_fma_f32 v[26:27], v[100:101], v[2:3], v[26:27] op_sel_hi:[1,0,1]
	v_pk_fma_f32 v[28:29], v[102:103], v[2:3], v[28:29] op_sel_hi:[1,0,1]
	v_pk_fma_f32 v[30:31], v[100:101], v[10:11], v[30:31] op_sel_hi:[1,0,1]
	v_pk_fma_f32 v[32:33], v[102:103], v[10:11], v[32:33] op_sel_hi:[1,0,1]
	v_pk_fma_f32 v[34:35], v[100:101], v[18:19], v[34:35] op_sel_hi:[1,0,1]
	v_pk_fma_f32 v[36:37], v[102:103], v[18:19], v[36:37] op_sel_hi:[1,0,1]
	global_load_dwordx4 v[100:103], v[180:181], off
	v_lshl_add_u64 v[180:181], s[40:41], 0, v[180:181]
	s_waitcnt vmcnt(19)
	v_pk_fma_f32 v[26:27], v[104:105], v[2:3], v[26:27] op_sel:[0,1,0]
	v_pk_fma_f32 v[28:29], v[106:107], v[2:3], v[28:29] op_sel:[0,1,0]
	v_pk_fma_f32 v[30:31], v[104:105], v[10:11], v[30:31] op_sel:[0,1,0]
	v_pk_fma_f32 v[32:33], v[106:107], v[10:11], v[32:33] op_sel:[0,1,0]
	v_pk_fma_f32 v[34:35], v[104:105], v[18:19], v[34:35] op_sel:[0,1,0]
	v_pk_fma_f32 v[36:37], v[106:107], v[18:19], v[36:37] op_sel:[0,1,0]
	global_load_dwordx4 v[104:107], v[180:181], off
	v_lshl_add_u64 v[180:181], s[40:41], 0, v[180:181]
	s_waitcnt vmcnt(19)
	v_pk_fma_f32 v[26:27], v[108:109], v[4:5], v[26:27] op_sel_hi:[1,0,1]
	v_pk_fma_f32 v[28:29], v[110:111], v[4:5], v[28:29] op_sel_hi:[1,0,1]
	v_pk_fma_f32 v[30:31], v[108:109], v[12:13], v[30:31] op_sel_hi:[1,0,1]
	v_pk_fma_f32 v[32:33], v[110:111], v[12:13], v[32:33] op_sel_hi:[1,0,1]
	v_pk_fma_f32 v[34:35], v[108:109], v[20:21], v[34:35] op_sel_hi:[1,0,1]
	v_pk_fma_f32 v[36:37], v[110:111], v[20:21], v[36:37] op_sel_hi:[1,0,1]
	global_load_dwordx4 v[108:111], v[180:181], off
	v_lshl_add_u64 v[180:181], s[40:41], 0, v[180:181]
	s_waitcnt vmcnt(19)
	v_pk_fma_f32 v[26:27], v[112:113], v[4:5], v[26:27] op_sel:[0,1,0]
	v_pk_fma_f32 v[28:29], v[114:115], v[4:5], v[28:29] op_sel:[0,1,0]
	v_pk_fma_f32 v[30:31], v[112:113], v[12:13], v[30:31] op_sel:[0,1,0]
	v_pk_fma_f32 v[32:33], v[114:115], v[12:13], v[32:33] op_sel:[0,1,0]
	v_pk_fma_f32 v[34:35], v[112:113], v[20:21], v[34:35] op_sel:[0,1,0]
	v_pk_fma_f32 v[36:37], v[114:115], v[20:21], v[36:37] op_sel:[0,1,0]
	global_load_dwordx4 v[112:115], v[180:181], off
	v_lshl_add_u64 v[180:181], s[40:41], 0, v[180:181]
	s_waitcnt vmcnt(19)
	v_pk_fma_f32 v[26:27], v[116:117], v[6:7], v[26:27] op_sel_hi:[1,0,1]
	v_pk_fma_f32 v[28:29], v[118:119], v[6:7], v[28:29] op_sel_hi:[1,0,1]
	v_pk_fma_f32 v[30:31], v[116:117], v[14:15], v[30:31] op_sel_hi:[1,0,1]
	v_pk_fma_f32 v[32:33], v[118:119], v[14:15], v[32:33] op_sel_hi:[1,0,1]
	v_pk_fma_f32 v[34:35], v[116:117], v[22:23], v[34:35] op_sel_hi:[1,0,1]
	v_pk_fma_f32 v[36:37], v[118:119], v[22:23], v[36:37] op_sel_hi:[1,0,1]
	global_load_dwordx4 v[116:119], v[180:181], off
	v_lshl_add_u64 v[180:181], s[40:41], 0, v[180:181]
	s_waitcnt vmcnt(19)
	v_pk_fma_f32 v[26:27], v[120:121], v[6:7], v[26:27] op_sel:[0,1,0]
	v_pk_fma_f32 v[28:29], v[122:123], v[6:7], v[28:29] op_sel:[0,1,0]
	v_pk_fma_f32 v[30:31], v[120:121], v[14:15], v[30:31] op_sel:[0,1,0]
	v_pk_fma_f32 v[32:33], v[122:123], v[14:15], v[32:33] op_sel:[0,1,0]
	v_pk_fma_f32 v[34:35], v[120:121], v[22:23], v[34:35] op_sel:[0,1,0]
	v_pk_fma_f32 v[36:37], v[122:123], v[22:23], v[36:37] op_sel:[0,1,0]
	global_load_dwordx4 v[120:123], v[180:181], off
	v_lshl_add_u64 v[180:181], s[40:41], 0, v[180:181]
	s_waitcnt vmcnt(19)
	v_pk_fma_f32 v[26:27], v[124:125], v[8:9], v[26:27] op_sel_hi:[1,0,1]
	v_pk_fma_f32 v[28:29], v[126:127], v[8:9], v[28:29] op_sel_hi:[1,0,1]
	v_pk_fma_f32 v[30:31], v[124:125], v[16:17], v[30:31] op_sel_hi:[1,0,1]
	v_pk_fma_f32 v[32:33], v[126:127], v[16:17], v[32:33] op_sel_hi:[1,0,1]
	v_pk_fma_f32 v[34:35], v[124:125], v[24:25], v[34:35] op_sel_hi:[1,0,1]
	v_pk_fma_f32 v[36:37], v[126:127], v[24:25], v[36:37] op_sel_hi:[1,0,1]
	global_load_dwordx4 v[124:127], v[180:181], off
	v_lshl_add_u64 v[180:181], s[40:41], 0, v[180:181]
	s_waitcnt vmcnt(19)
	v_pk_fma_f32 v[26:27], v[128:129], v[8:9], v[26:27] op_sel:[0,1,0]
	v_pk_fma_f32 v[28:29], v[130:131], v[8:9], v[28:29] op_sel:[0,1,0]
	v_pk_fma_f32 v[30:31], v[128:129], v[16:17], v[30:31] op_sel:[0,1,0]
	v_pk_fma_f32 v[32:33], v[130:131], v[16:17], v[32:33] op_sel:[0,1,0]
	v_pk_fma_f32 v[34:35], v[128:129], v[24:25], v[34:35] op_sel:[0,1,0]
	v_pk_fma_f32 v[36:37], v[130:131], v[24:25], v[36:37] op_sel:[0,1,0]
	global_load_dwordx4 v[128:131], v[180:181], off
	v_lshl_add_u64 v[180:181], s[40:41], 0, v[180:181]
	ds_read_b128 v[2:5], v46 offset:64
	ds_read_b128 v[6:9], v46 offset:80
	ds_read_b128 v[10:13], v46 offset:4160
	ds_read_b128 v[14:17], v46 offset:4176
	ds_read_b128 v[18:21], v46 offset:8256
	ds_read_b128 v[22:25], v46 offset:8272
	s_waitcnt lgkmcnt(6)
	s_waitcnt vmcnt(19)
	v_pk_fma_f32 v[26:27], v[132:133], v[50:51], v[26:27] op_sel_hi:[1,0,1]
	v_pk_fma_f32 v[28:29], v[134:135], v[50:51], v[28:29] op_sel_hi:[1,0,1]
	v_pk_fma_f32 v[30:31], v[132:133], v[58:59], v[30:31] op_sel_hi:[1,0,1]
	v_pk_fma_f32 v[32:33], v[134:135], v[58:59], v[32:33] op_sel_hi:[1,0,1]
	v_pk_fma_f32 v[34:35], v[132:133], v[66:67], v[34:35] op_sel_hi:[1,0,1]
	v_pk_fma_f32 v[36:37], v[134:135], v[66:67], v[36:37] op_sel_hi:[1,0,1]
	global_load_dwordx4 v[132:135], v[180:181], off
	v_lshl_add_u64 v[180:181], s[40:41], 0, v[180:181]
	s_waitcnt vmcnt(19)
	v_pk_fma_f32 v[26:27], v[136:137], v[50:51], v[26:27] op_sel:[0,1,0]
	v_pk_fma_f32 v[28:29], v[138:139], v[50:51], v[28:29] op_sel:[0,1,0]
	v_pk_fma_f32 v[30:31], v[136:137], v[58:59], v[30:31] op_sel:[0,1,0]
	v_pk_fma_f32 v[32:33], v[138:139], v[58:59], v[32:33] op_sel:[0,1,0]
	v_pk_fma_f32 v[34:35], v[136:137], v[66:67], v[34:35] op_sel:[0,1,0]
	v_pk_fma_f32 v[36:37], v[138:139], v[66:67], v[36:37] op_sel:[0,1,0]
	global_load_dwordx4 v[136:139], v[180:181], off
	v_lshl_add_u64 v[180:181], s[40:41], 0, v[180:181]
	s_waitcnt vmcnt(19)
	v_pk_fma_f32 v[26:27], v[140:141], v[52:53], v[26:27] op_sel_hi:[1,0,1]
	v_pk_fma_f32 v[28:29], v[142:143], v[52:53], v[28:29] op_sel_hi:[1,0,1]
	v_pk_fma_f32 v[30:31], v[140:141], v[60:61], v[30:31] op_sel_hi:[1,0,1]
	v_pk_fma_f32 v[32:33], v[142:143], v[60:61], v[32:33] op_sel_hi:[1,0,1]
	v_pk_fma_f32 v[34:35], v[140:141], v[68:69], v[34:35] op_sel_hi:[1,0,1]
	v_pk_fma_f32 v[36:37], v[142:143], v[68:69], v[36:37] op_sel_hi:[1,0,1]
	global_load_dwordx4 v[140:143], v[180:181], off
	v_lshl_add_u64 v[180:181], s[40:41], 0, v[180:181]
	s_waitcnt vmcnt(19)
	v_pk_fma_f32 v[26:27], v[144:145], v[52:53], v[26:27] op_sel:[0,1,0]
	v_pk_fma_f32 v[28:29], v[146:147], v[52:53], v[28:29] op_sel:[0,1,0]
	v_pk_fma_f32 v[30:31], v[144:145], v[60:61], v[30:31] op_sel:[0,1,0]
	v_pk_fma_f32 v[32:33], v[146:147], v[60:61], v[32:33] op_sel:[0,1,0]
	v_pk_fma_f32 v[34:35], v[144:145], v[68:69], v[34:35] op_sel:[0,1,0]
	v_pk_fma_f32 v[36:37], v[146:147], v[68:69], v[36:37] op_sel:[0,1,0]
	global_load_dwordx4 v[144:147], v[180:181], off
	v_lshl_add_u64 v[180:181], s[40:41], 0, v[180:181]
	s_waitcnt vmcnt(19)
	v_pk_fma_f32 v[26:27], v[148:149], v[54:55], v[26:27] op_sel_hi:[1,0,1]
	v_pk_fma_f32 v[28:29], v[150:151], v[54:55], v[28:29] op_sel_hi:[1,0,1]
	v_pk_fma_f32 v[30:31], v[148:149], v[62:63], v[30:31] op_sel_hi:[1,0,1]
	v_pk_fma_f32 v[32:33], v[150:151], v[62:63], v[32:33] op_sel_hi:[1,0,1]
	v_pk_fma_f32 v[34:35], v[148:149], v[70:71], v[34:35] op_sel_hi:[1,0,1]
	v_pk_fma_f32 v[36:37], v[150:151], v[70:71], v[36:37] op_sel_hi:[1,0,1]
	global_load_dwordx4 v[148:151], v[180:181], off
	v_lshl_add_u64 v[180:181], s[40:41], 0, v[180:181]
	s_waitcnt vmcnt(19)
	v_pk_fma_f32 v[26:27], v[152:153], v[54:55], v[26:27] op_sel:[0,1,0]
	v_pk_fma_f32 v[28:29], v[154:155], v[54:55], v[28:29] op_sel:[0,1,0]
	v_pk_fma_f32 v[30:31], v[152:153], v[62:63], v[30:31] op_sel:[0,1,0]
	v_pk_fma_f32 v[32:33], v[154:155], v[62:63], v[32:33] op_sel:[0,1,0]
	v_pk_fma_f32 v[34:35], v[152:153], v[70:71], v[34:35] op_sel:[0,1,0]
	v_pk_fma_f32 v[36:37], v[154:155], v[70:71], v[36:37] op_sel:[0,1,0]
	global_load_dwordx4 v[152:155], v[180:181], off
	v_lshl_add_u64 v[180:181], s[40:41], 0, v[180:181]
	s_waitcnt vmcnt(19)
	v_pk_fma_f32 v[26:27], v[156:157], v[56:57], v[26:27] op_sel_hi:[1,0,1]
	v_pk_fma_f32 v[28:29], v[158:159], v[56:57], v[28:29] op_sel_hi:[1,0,1]
	v_pk_fma_f32 v[30:31], v[156:157], v[64:65], v[30:31] op_sel_hi:[1,0,1]
	v_pk_fma_f32 v[32:33], v[158:159], v[64:65], v[32:33] op_sel_hi:[1,0,1]
	v_pk_fma_f32 v[34:35], v[156:157], v[72:73], v[34:35] op_sel_hi:[1,0,1]
	v_pk_fma_f32 v[36:37], v[158:159], v[72:73], v[36:37] op_sel_hi:[1,0,1]
	global_load_dwordx4 v[156:159], v[180:181], off
	v_lshl_add_u64 v[180:181], s[40:41], 0, v[180:181]
	s_waitcnt vmcnt(19)
	v_pk_fma_f32 v[26:27], v[160:161], v[56:57], v[26:27] op_sel:[0,1,0]
	v_pk_fma_f32 v[28:29], v[162:163], v[56:57], v[28:29] op_sel:[0,1,0]
	v_pk_fma_f32 v[30:31], v[160:161], v[64:65], v[30:31] op_sel:[0,1,0]
	v_pk_fma_f32 v[32:33], v[162:163], v[64:65], v[32:33] op_sel:[0,1,0]
	v_pk_fma_f32 v[34:35], v[160:161], v[72:73], v[34:35] op_sel:[0,1,0]
	v_pk_fma_f32 v[36:37], v[162:163], v[72:73], v[36:37] op_sel:[0,1,0]
	global_load_dwordx4 v[160:163], v[180:181], off
	v_lshl_add_u64 v[180:181], s[40:41], 0, v[180:181]
	ds_read_b128 v[50:53], v46 offset:96
	ds_read_b128 v[54:57], v46 offset:112
	ds_read_b128 v[58:61], v46 offset:4192
	ds_read_b128 v[62:65], v46 offset:4208
	ds_read_b128 v[66:69], v46 offset:8288
	ds_read_b128 v[70:73], v46 offset:8304
	s_waitcnt lgkmcnt(6)
	s_waitcnt vmcnt(19)
	v_pk_fma_f32 v[26:27], v[164:165], v[2:3], v[26:27] op_sel_hi:[1,0,1]
	v_pk_fma_f32 v[28:29], v[166:167], v[2:3], v[28:29] op_sel_hi:[1,0,1]
	v_pk_fma_f32 v[30:31], v[164:165], v[10:11], v[30:31] op_sel_hi:[1,0,1]
	v_pk_fma_f32 v[32:33], v[166:167], v[10:11], v[32:33] op_sel_hi:[1,0,1]
	v_pk_fma_f32 v[34:35], v[164:165], v[18:19], v[34:35] op_sel_hi:[1,0,1]
	v_pk_fma_f32 v[36:37], v[166:167], v[18:19], v[36:37] op_sel_hi:[1,0,1]
	global_load_dwordx4 v[164:167], v[180:181], off
	v_lshl_add_u64 v[180:181], s[40:41], 0, v[180:181]
	s_waitcnt vmcnt(19)
	v_pk_fma_f32 v[26:27], v[168:169], v[2:3], v[26:27] op_sel:[0,1,0]
	v_pk_fma_f32 v[28:29], v[170:171], v[2:3], v[28:29] op_sel:[0,1,0]
	v_pk_fma_f32 v[30:31], v[168:169], v[10:11], v[30:31] op_sel:[0,1,0]
	v_pk_fma_f32 v[32:33], v[170:171], v[10:11], v[32:33] op_sel:[0,1,0]
	v_pk_fma_f32 v[34:35], v[168:169], v[18:19], v[34:35] op_sel:[0,1,0]
	v_pk_fma_f32 v[36:37], v[170:171], v[18:19], v[36:37] op_sel:[0,1,0]
	global_load_dwordx4 v[168:171], v[180:181], off
	v_lshl_add_u64 v[180:181], s[40:41], 0, v[180:181]
	s_waitcnt vmcnt(19)
	v_pk_fma_f32 v[26:27], v[172:173], v[4:5], v[26:27] op_sel_hi:[1,0,1]
	v_pk_fma_f32 v[28:29], v[174:175], v[4:5], v[28:29] op_sel_hi:[1,0,1]
	v_pk_fma_f32 v[30:31], v[172:173], v[12:13], v[30:31] op_sel_hi:[1,0,1]
	v_pk_fma_f32 v[32:33], v[174:175], v[12:13], v[32:33] op_sel_hi:[1,0,1]
	v_pk_fma_f32 v[34:35], v[172:173], v[20:21], v[34:35] op_sel_hi:[1,0,1]
	v_pk_fma_f32 v[36:37], v[174:175], v[20:21], v[36:37] op_sel_hi:[1,0,1]
	global_load_dwordx4 v[172:175], v[180:181], off
	v_lshl_add_u64 v[180:181], s[40:41], 0, v[180:181]
	s_waitcnt vmcnt(19)
	v_pk_fma_f32 v[26:27], v[176:177], v[4:5], v[26:27] op_sel:[0,1,0]
	v_pk_fma_f32 v[28:29], v[178:179], v[4:5], v[28:29] op_sel:[0,1,0]
	v_pk_fma_f32 v[30:31], v[176:177], v[12:13], v[30:31] op_sel:[0,1,0]
	v_pk_fma_f32 v[32:33], v[178:179], v[12:13], v[32:33] op_sel:[0,1,0]
	v_pk_fma_f32 v[34:35], v[176:177], v[20:21], v[34:35] op_sel:[0,1,0]
	v_pk_fma_f32 v[36:37], v[178:179], v[20:21], v[36:37] op_sel:[0,1,0]
	global_load_dwordx4 v[176:179], v[180:181], off
	v_lshl_add_u64 v[180:181], s[40:41], 0, v[180:181]
	s_waitcnt vmcnt(19)
	v_pk_fma_f32 v[26:27], v[100:101], v[6:7], v[26:27] op_sel_hi:[1,0,1]
	v_pk_fma_f32 v[28:29], v[102:103], v[6:7], v[28:29] op_sel_hi:[1,0,1]
	v_pk_fma_f32 v[30:31], v[100:101], v[14:15], v[30:31] op_sel_hi:[1,0,1]
	v_pk_fma_f32 v[32:33], v[102:103], v[14:15], v[32:33] op_sel_hi:[1,0,1]
	v_pk_fma_f32 v[34:35], v[100:101], v[22:23], v[34:35] op_sel_hi:[1,0,1]
	v_pk_fma_f32 v[36:37], v[102:103], v[22:23], v[36:37] op_sel_hi:[1,0,1]
	global_load_dwordx4 v[100:103], v[180:181], off
	v_lshl_add_u64 v[180:181], s[40:41], 0, v[180:181]
	s_waitcnt vmcnt(19)
	v_pk_fma_f32 v[26:27], v[104:105], v[6:7], v[26:27] op_sel:[0,1,0]
	v_pk_fma_f32 v[28:29], v[106:107], v[6:7], v[28:29] op_sel:[0,1,0]
	v_pk_fma_f32 v[30:31], v[104:105], v[14:15], v[30:31] op_sel:[0,1,0]
	v_pk_fma_f32 v[32:33], v[106:107], v[14:15], v[32:33] op_sel:[0,1,0]
	v_pk_fma_f32 v[34:35], v[104:105], v[22:23], v[34:35] op_sel:[0,1,0]
	v_pk_fma_f32 v[36:37], v[106:107], v[22:23], v[36:37] op_sel:[0,1,0]
	global_load_dwordx4 v[104:107], v[180:181], off
	v_lshl_add_u64 v[180:181], s[40:41], 0, v[180:181]
	s_waitcnt vmcnt(19)
	v_pk_fma_f32 v[26:27], v[108:109], v[8:9], v[26:27] op_sel_hi:[1,0,1]
	v_pk_fma_f32 v[28:29], v[110:111], v[8:9], v[28:29] op_sel_hi:[1,0,1]
	v_pk_fma_f32 v[30:31], v[108:109], v[16:17], v[30:31] op_sel_hi:[1,0,1]
	v_pk_fma_f32 v[32:33], v[110:111], v[16:17], v[32:33] op_sel_hi:[1,0,1]
	v_pk_fma_f32 v[34:35], v[108:109], v[24:25], v[34:35] op_sel_hi:[1,0,1]
	v_pk_fma_f32 v[36:37], v[110:111], v[24:25], v[36:37] op_sel_hi:[1,0,1]
	global_load_dwordx4 v[108:111], v[180:181], off
	v_lshl_add_u64 v[180:181], s[40:41], 0, v[180:181]
	s_waitcnt vmcnt(19)
	v_pk_fma_f32 v[26:27], v[112:113], v[8:9], v[26:27] op_sel:[0,1,0]
	v_pk_fma_f32 v[28:29], v[114:115], v[8:9], v[28:29] op_sel:[0,1,0]
	v_pk_fma_f32 v[30:31], v[112:113], v[16:17], v[30:31] op_sel:[0,1,0]
	v_pk_fma_f32 v[32:33], v[114:115], v[16:17], v[32:33] op_sel:[0,1,0]
	v_pk_fma_f32 v[34:35], v[112:113], v[24:25], v[34:35] op_sel:[0,1,0]
	v_pk_fma_f32 v[36:37], v[114:115], v[24:25], v[36:37] op_sel:[0,1,0]
	global_load_dwordx4 v[112:115], v[180:181], off
	v_lshl_add_u64 v[180:181], s[40:41], 0, v[180:181]
	ds_read_b128 v[2:5], v46 offset:128
	ds_read_b128 v[6:9], v46 offset:144
	ds_read_b128 v[10:13], v46 offset:4224
	ds_read_b128 v[14:17], v46 offset:4240
	ds_read_b128 v[18:21], v46 offset:8320
	ds_read_b128 v[22:25], v46 offset:8336
	s_waitcnt lgkmcnt(6)
	s_waitcnt vmcnt(19)
	v_pk_fma_f32 v[26:27], v[116:117], v[50:51], v[26:27] op_sel_hi:[1,0,1]
	v_pk_fma_f32 v[28:29], v[118:119], v[50:51], v[28:29] op_sel_hi:[1,0,1]
	v_pk_fma_f32 v[30:31], v[116:117], v[58:59], v[30:31] op_sel_hi:[1,0,1]
	v_pk_fma_f32 v[32:33], v[118:119], v[58:59], v[32:33] op_sel_hi:[1,0,1]
	v_pk_fma_f32 v[34:35], v[116:117], v[66:67], v[34:35] op_sel_hi:[1,0,1]
	v_pk_fma_f32 v[36:37], v[118:119], v[66:67], v[36:37] op_sel_hi:[1,0,1]
	global_load_dwordx4 v[116:119], v[180:181], off
	v_lshl_add_u64 v[180:181], s[40:41], 0, v[180:181]
	s_waitcnt vmcnt(19)
	v_pk_fma_f32 v[26:27], v[120:121], v[50:51], v[26:27] op_sel:[0,1,0]
	v_pk_fma_f32 v[28:29], v[122:123], v[50:51], v[28:29] op_sel:[0,1,0]
	v_pk_fma_f32 v[30:31], v[120:121], v[58:59], v[30:31] op_sel:[0,1,0]
	v_pk_fma_f32 v[32:33], v[122:123], v[58:59], v[32:33] op_sel:[0,1,0]
	v_pk_fma_f32 v[34:35], v[120:121], v[66:67], v[34:35] op_sel:[0,1,0]
	v_pk_fma_f32 v[36:37], v[122:123], v[66:67], v[36:37] op_sel:[0,1,0]
	global_load_dwordx4 v[120:123], v[180:181], off
	v_lshl_add_u64 v[180:181], s[40:41], 0, v[180:181]
	s_waitcnt vmcnt(19)
	v_pk_fma_f32 v[26:27], v[124:125], v[52:53], v[26:27] op_sel_hi:[1,0,1]
	v_pk_fma_f32 v[28:29], v[126:127], v[52:53], v[28:29] op_sel_hi:[1,0,1]
	v_pk_fma_f32 v[30:31], v[124:125], v[60:61], v[30:31] op_sel_hi:[1,0,1]
	v_pk_fma_f32 v[32:33], v[126:127], v[60:61], v[32:33] op_sel_hi:[1,0,1]
	v_pk_fma_f32 v[34:35], v[124:125], v[68:69], v[34:35] op_sel_hi:[1,0,1]
	v_pk_fma_f32 v[36:37], v[126:127], v[68:69], v[36:37] op_sel_hi:[1,0,1]
	global_load_dwordx4 v[124:127], v[180:181], off
	v_lshl_add_u64 v[180:181], s[40:41], 0, v[180:181]
	s_waitcnt vmcnt(19)
	v_pk_fma_f32 v[26:27], v[128:129], v[52:53], v[26:27] op_sel:[0,1,0]
	v_pk_fma_f32 v[28:29], v[130:131], v[52:53], v[28:29] op_sel:[0,1,0]
	v_pk_fma_f32 v[30:31], v[128:129], v[60:61], v[30:31] op_sel:[0,1,0]
	v_pk_fma_f32 v[32:33], v[130:131], v[60:61], v[32:33] op_sel:[0,1,0]
	v_pk_fma_f32 v[34:35], v[128:129], v[68:69], v[34:35] op_sel:[0,1,0]
	v_pk_fma_f32 v[36:37], v[130:131], v[68:69], v[36:37] op_sel:[0,1,0]
	global_load_dwordx4 v[128:131], v[180:181], off
	v_lshl_add_u64 v[180:181], s[40:41], 0, v[180:181]
	s_waitcnt vmcnt(19)
	v_pk_fma_f32 v[26:27], v[132:133], v[54:55], v[26:27] op_sel_hi:[1,0,1]
	v_pk_fma_f32 v[28:29], v[134:135], v[54:55], v[28:29] op_sel_hi:[1,0,1]
	v_pk_fma_f32 v[30:31], v[132:133], v[62:63], v[30:31] op_sel_hi:[1,0,1]
	v_pk_fma_f32 v[32:33], v[134:135], v[62:63], v[32:33] op_sel_hi:[1,0,1]
	v_pk_fma_f32 v[34:35], v[132:133], v[70:71], v[34:35] op_sel_hi:[1,0,1]
	v_pk_fma_f32 v[36:37], v[134:135], v[70:71], v[36:37] op_sel_hi:[1,0,1]
	global_load_dwordx4 v[132:135], v[180:181], off
	v_lshl_add_u64 v[180:181], s[40:41], 0, v[180:181]
	s_waitcnt vmcnt(19)
	v_pk_fma_f32 v[26:27], v[136:137], v[54:55], v[26:27] op_sel:[0,1,0]
	v_pk_fma_f32 v[28:29], v[138:139], v[54:55], v[28:29] op_sel:[0,1,0]
	v_pk_fma_f32 v[30:31], v[136:137], v[62:63], v[30:31] op_sel:[0,1,0]
	v_pk_fma_f32 v[32:33], v[138:139], v[62:63], v[32:33] op_sel:[0,1,0]
	v_pk_fma_f32 v[34:35], v[136:137], v[70:71], v[34:35] op_sel:[0,1,0]
	v_pk_fma_f32 v[36:37], v[138:139], v[70:71], v[36:37] op_sel:[0,1,0]
	global_load_dwordx4 v[136:139], v[180:181], off
	v_lshl_add_u64 v[180:181], s[40:41], 0, v[180:181]
	s_waitcnt vmcnt(19)
	v_pk_fma_f32 v[26:27], v[140:141], v[56:57], v[26:27] op_sel_hi:[1,0,1]
	v_pk_fma_f32 v[28:29], v[142:143], v[56:57], v[28:29] op_sel_hi:[1,0,1]
	v_pk_fma_f32 v[30:31], v[140:141], v[64:65], v[30:31] op_sel_hi:[1,0,1]
	v_pk_fma_f32 v[32:33], v[142:143], v[64:65], v[32:33] op_sel_hi:[1,0,1]
	v_pk_fma_f32 v[34:35], v[140:141], v[72:73], v[34:35] op_sel_hi:[1,0,1]
	v_pk_fma_f32 v[36:37], v[142:143], v[72:73], v[36:37] op_sel_hi:[1,0,1]
	global_load_dwordx4 v[140:143], v[180:181], off
	v_lshl_add_u64 v[180:181], s[40:41], 0, v[180:181]
	s_waitcnt vmcnt(19)
	v_pk_fma_f32 v[26:27], v[144:145], v[56:57], v[26:27] op_sel:[0,1,0]
	v_pk_fma_f32 v[28:29], v[146:147], v[56:57], v[28:29] op_sel:[0,1,0]
	v_pk_fma_f32 v[30:31], v[144:145], v[64:65], v[30:31] op_sel:[0,1,0]
	v_pk_fma_f32 v[32:33], v[146:147], v[64:65], v[32:33] op_sel:[0,1,0]
	v_pk_fma_f32 v[34:35], v[144:145], v[72:73], v[34:35] op_sel:[0,1,0]
	v_pk_fma_f32 v[36:37], v[146:147], v[72:73], v[36:37] op_sel:[0,1,0]
	global_load_dwordx4 v[144:147], v[180:181], off
	v_lshl_add_u64 v[180:181], s[40:41], 0, v[180:181]
	ds_read_b128 v[50:53], v46 offset:160
	ds_read_b128 v[54:57], v46 offset:176
	ds_read_b128 v[58:61], v46 offset:4256
	ds_read_b128 v[62:65], v46 offset:4272
	ds_read_b128 v[66:69], v46 offset:8352
	ds_read_b128 v[70:73], v46 offset:8368
	s_waitcnt lgkmcnt(6)
	s_waitcnt vmcnt(19)
	v_pk_fma_f32 v[26:27], v[148:149], v[2:3], v[26:27] op_sel_hi:[1,0,1]
	v_pk_fma_f32 v[28:29], v[150:151], v[2:3], v[28:29] op_sel_hi:[1,0,1]
	v_pk_fma_f32 v[30:31], v[148:149], v[10:11], v[30:31] op_sel_hi:[1,0,1]
	v_pk_fma_f32 v[32:33], v[150:151], v[10:11], v[32:33] op_sel_hi:[1,0,1]
	v_pk_fma_f32 v[34:35], v[148:149], v[18:19], v[34:35] op_sel_hi:[1,0,1]
	v_pk_fma_f32 v[36:37], v[150:151], v[18:19], v[36:37] op_sel_hi:[1,0,1]
	global_load_dwordx4 v[148:151], v[180:181], off
	v_lshl_add_u64 v[180:181], s[40:41], 0, v[180:181]
	s_waitcnt vmcnt(19)
	v_pk_fma_f32 v[26:27], v[152:153], v[2:3], v[26:27] op_sel:[0,1,0]
	v_pk_fma_f32 v[28:29], v[154:155], v[2:3], v[28:29] op_sel:[0,1,0]
	v_pk_fma_f32 v[30:31], v[152:153], v[10:11], v[30:31] op_sel:[0,1,0]
	v_pk_fma_f32 v[32:33], v[154:155], v[10:11], v[32:33] op_sel:[0,1,0]
	v_pk_fma_f32 v[34:35], v[152:153], v[18:19], v[34:35] op_sel:[0,1,0]
	v_pk_fma_f32 v[36:37], v[154:155], v[18:19], v[36:37] op_sel:[0,1,0]
	global_load_dwordx4 v[152:155], v[180:181], off
	v_lshl_add_u64 v[180:181], s[40:41], 0, v[180:181]
	s_waitcnt vmcnt(19)
	v_pk_fma_f32 v[26:27], v[156:157], v[4:5], v[26:27] op_sel_hi:[1,0,1]
	v_pk_fma_f32 v[28:29], v[158:159], v[4:5], v[28:29] op_sel_hi:[1,0,1]
	v_pk_fma_f32 v[30:31], v[156:157], v[12:13], v[30:31] op_sel_hi:[1,0,1]
	v_pk_fma_f32 v[32:33], v[158:159], v[12:13], v[32:33] op_sel_hi:[1,0,1]
	v_pk_fma_f32 v[34:35], v[156:157], v[20:21], v[34:35] op_sel_hi:[1,0,1]
	v_pk_fma_f32 v[36:37], v[158:159], v[20:21], v[36:37] op_sel_hi:[1,0,1]
	global_load_dwordx4 v[156:159], v[180:181], off
	v_lshl_add_u64 v[180:181], s[40:41], 0, v[180:181]
	s_waitcnt vmcnt(19)
	v_pk_fma_f32 v[26:27], v[160:161], v[4:5], v[26:27] op_sel:[0,1,0]
	v_pk_fma_f32 v[28:29], v[162:163], v[4:5], v[28:29] op_sel:[0,1,0]
	v_pk_fma_f32 v[30:31], v[160:161], v[12:13], v[30:31] op_sel:[0,1,0]
	v_pk_fma_f32 v[32:33], v[162:163], v[12:13], v[32:33] op_sel:[0,1,0]
	v_pk_fma_f32 v[34:35], v[160:161], v[20:21], v[34:35] op_sel:[0,1,0]
	v_pk_fma_f32 v[36:37], v[162:163], v[20:21], v[36:37] op_sel:[0,1,0]
	global_load_dwordx4 v[160:163], v[180:181], off
	v_lshl_add_u64 v[180:181], s[40:41], 0, v[180:181]
	s_waitcnt vmcnt(19)
	v_pk_fma_f32 v[26:27], v[164:165], v[6:7], v[26:27] op_sel_hi:[1,0,1]
	v_pk_fma_f32 v[28:29], v[166:167], v[6:7], v[28:29] op_sel_hi:[1,0,1]
	v_pk_fma_f32 v[30:31], v[164:165], v[14:15], v[30:31] op_sel_hi:[1,0,1]
	v_pk_fma_f32 v[32:33], v[166:167], v[14:15], v[32:33] op_sel_hi:[1,0,1]
	v_pk_fma_f32 v[34:35], v[164:165], v[22:23], v[34:35] op_sel_hi:[1,0,1]
	v_pk_fma_f32 v[36:37], v[166:167], v[22:23], v[36:37] op_sel_hi:[1,0,1]
	global_load_dwordx4 v[164:167], v[180:181], off
	v_lshl_add_u64 v[180:181], s[40:41], 0, v[180:181]
	s_waitcnt vmcnt(19)
	v_pk_fma_f32 v[26:27], v[168:169], v[6:7], v[26:27] op_sel:[0,1,0]
	v_pk_fma_f32 v[28:29], v[170:171], v[6:7], v[28:29] op_sel:[0,1,0]
	v_pk_fma_f32 v[30:31], v[168:169], v[14:15], v[30:31] op_sel:[0,1,0]
	v_pk_fma_f32 v[32:33], v[170:171], v[14:15], v[32:33] op_sel:[0,1,0]
	v_pk_fma_f32 v[34:35], v[168:169], v[22:23], v[34:35] op_sel:[0,1,0]
	v_pk_fma_f32 v[36:37], v[170:171], v[22:23], v[36:37] op_sel:[0,1,0]
	global_load_dwordx4 v[168:171], v[180:181], off
	v_lshl_add_u64 v[180:181], s[40:41], 0, v[180:181]
	s_waitcnt vmcnt(19)
	v_pk_fma_f32 v[26:27], v[172:173], v[8:9], v[26:27] op_sel_hi:[1,0,1]
	v_pk_fma_f32 v[28:29], v[174:175], v[8:9], v[28:29] op_sel_hi:[1,0,1]
	v_pk_fma_f32 v[30:31], v[172:173], v[16:17], v[30:31] op_sel_hi:[1,0,1]
	v_pk_fma_f32 v[32:33], v[174:175], v[16:17], v[32:33] op_sel_hi:[1,0,1]
	v_pk_fma_f32 v[34:35], v[172:173], v[24:25], v[34:35] op_sel_hi:[1,0,1]
	v_pk_fma_f32 v[36:37], v[174:175], v[24:25], v[36:37] op_sel_hi:[1,0,1]
	global_load_dwordx4 v[172:175], v[180:181], off
	v_lshl_add_u64 v[180:181], s[40:41], 0, v[180:181]
	s_waitcnt vmcnt(19)
	v_pk_fma_f32 v[26:27], v[176:177], v[8:9], v[26:27] op_sel:[0,1,0]
	v_pk_fma_f32 v[28:29], v[178:179], v[8:9], v[28:29] op_sel:[0,1,0]
	v_pk_fma_f32 v[30:31], v[176:177], v[16:17], v[30:31] op_sel:[0,1,0]
	v_pk_fma_f32 v[32:33], v[178:179], v[16:17], v[32:33] op_sel:[0,1,0]
	v_pk_fma_f32 v[34:35], v[176:177], v[24:25], v[34:35] op_sel:[0,1,0]
	v_pk_fma_f32 v[36:37], v[178:179], v[24:25], v[36:37] op_sel:[0,1,0]
	global_load_dwordx4 v[176:179], v[180:181], off
	v_lshl_add_u64 v[180:181], s[40:41], 0, v[180:181]
	ds_read_b128 v[2:5], v46 offset:192
	ds_read_b128 v[6:9], v46 offset:208
	ds_read_b128 v[10:13], v46 offset:4288
	ds_read_b128 v[14:17], v46 offset:4304
	ds_read_b128 v[18:21], v46 offset:8384
	ds_read_b128 v[22:25], v46 offset:8400
	s_waitcnt lgkmcnt(6)
	s_waitcnt vmcnt(19)
	v_pk_fma_f32 v[26:27], v[100:101], v[50:51], v[26:27] op_sel_hi:[1,0,1]
	v_pk_fma_f32 v[28:29], v[102:103], v[50:51], v[28:29] op_sel_hi:[1,0,1]
	v_pk_fma_f32 v[30:31], v[100:101], v[58:59], v[30:31] op_sel_hi:[1,0,1]
	v_pk_fma_f32 v[32:33], v[102:103], v[58:59], v[32:33] op_sel_hi:[1,0,1]
	v_pk_fma_f32 v[34:35], v[100:101], v[66:67], v[34:35] op_sel_hi:[1,0,1]
	v_pk_fma_f32 v[36:37], v[102:103], v[66:67], v[36:37] op_sel_hi:[1,0,1]
	global_load_dwordx4 v[100:103], v[180:181], off
	v_lshl_add_u64 v[180:181], s[40:41], 0, v[180:181]
	s_waitcnt vmcnt(19)
	v_pk_fma_f32 v[26:27], v[104:105], v[50:51], v[26:27] op_sel:[0,1,0]
	v_pk_fma_f32 v[28:29], v[106:107], v[50:51], v[28:29] op_sel:[0,1,0]
	v_pk_fma_f32 v[30:31], v[104:105], v[58:59], v[30:31] op_sel:[0,1,0]
	v_pk_fma_f32 v[32:33], v[106:107], v[58:59], v[32:33] op_sel:[0,1,0]
	v_pk_fma_f32 v[34:35], v[104:105], v[66:67], v[34:35] op_sel:[0,1,0]
	v_pk_fma_f32 v[36:37], v[106:107], v[66:67], v[36:37] op_sel:[0,1,0]
	global_load_dwordx4 v[104:107], v[180:181], off
	v_lshl_add_u64 v[180:181], s[40:41], 0, v[180:181]
	s_waitcnt vmcnt(19)
	v_pk_fma_f32 v[26:27], v[108:109], v[52:53], v[26:27] op_sel_hi:[1,0,1]
	v_pk_fma_f32 v[28:29], v[110:111], v[52:53], v[28:29] op_sel_hi:[1,0,1]
	v_pk_fma_f32 v[30:31], v[108:109], v[60:61], v[30:31] op_sel_hi:[1,0,1]
	v_pk_fma_f32 v[32:33], v[110:111], v[60:61], v[32:33] op_sel_hi:[1,0,1]
	v_pk_fma_f32 v[34:35], v[108:109], v[68:69], v[34:35] op_sel_hi:[1,0,1]
	v_pk_fma_f32 v[36:37], v[110:111], v[68:69], v[36:37] op_sel_hi:[1,0,1]
	global_load_dwordx4 v[108:111], v[180:181], off
	v_lshl_add_u64 v[180:181], s[40:41], 0, v[180:181]
	s_waitcnt vmcnt(19)
	v_pk_fma_f32 v[26:27], v[112:113], v[52:53], v[26:27] op_sel:[0,1,0]
	v_pk_fma_f32 v[28:29], v[114:115], v[52:53], v[28:29] op_sel:[0,1,0]
	v_pk_fma_f32 v[30:31], v[112:113], v[60:61], v[30:31] op_sel:[0,1,0]
	v_pk_fma_f32 v[32:33], v[114:115], v[60:61], v[32:33] op_sel:[0,1,0]
	v_pk_fma_f32 v[34:35], v[112:113], v[68:69], v[34:35] op_sel:[0,1,0]
	v_pk_fma_f32 v[36:37], v[114:115], v[68:69], v[36:37] op_sel:[0,1,0]
	global_load_dwordx4 v[112:115], v[180:181], off
	v_lshl_add_u64 v[180:181], s[40:41], 0, v[180:181]
	s_waitcnt vmcnt(19)
	v_pk_fma_f32 v[26:27], v[116:117], v[54:55], v[26:27] op_sel_hi:[1,0,1]
	v_pk_fma_f32 v[28:29], v[118:119], v[54:55], v[28:29] op_sel_hi:[1,0,1]
	v_pk_fma_f32 v[30:31], v[116:117], v[62:63], v[30:31] op_sel_hi:[1,0,1]
	v_pk_fma_f32 v[32:33], v[118:119], v[62:63], v[32:33] op_sel_hi:[1,0,1]
	v_pk_fma_f32 v[34:35], v[116:117], v[70:71], v[34:35] op_sel_hi:[1,0,1]
	v_pk_fma_f32 v[36:37], v[118:119], v[70:71], v[36:37] op_sel_hi:[1,0,1]
	s_waitcnt vmcnt(18)
	v_pk_fma_f32 v[26:27], v[120:121], v[54:55], v[26:27] op_sel:[0,1,0]
	v_pk_fma_f32 v[28:29], v[122:123], v[54:55], v[28:29] op_sel:[0,1,0]
	v_pk_fma_f32 v[30:31], v[120:121], v[62:63], v[30:31] op_sel:[0,1,0]
	v_pk_fma_f32 v[32:33], v[122:123], v[62:63], v[32:33] op_sel:[0,1,0]
	v_pk_fma_f32 v[34:35], v[120:121], v[70:71], v[34:35] op_sel:[0,1,0]
	v_pk_fma_f32 v[36:37], v[122:123], v[70:71], v[36:37] op_sel:[0,1,0]
	s_waitcnt vmcnt(17)
	v_pk_fma_f32 v[26:27], v[124:125], v[56:57], v[26:27] op_sel_hi:[1,0,1]
	v_pk_fma_f32 v[28:29], v[126:127], v[56:57], v[28:29] op_sel_hi:[1,0,1]
	v_pk_fma_f32 v[30:31], v[124:125], v[64:65], v[30:31] op_sel_hi:[1,0,1]
	v_pk_fma_f32 v[32:33], v[126:127], v[64:65], v[32:33] op_sel_hi:[1,0,1]
	v_pk_fma_f32 v[34:35], v[124:125], v[72:73], v[34:35] op_sel_hi:[1,0,1]
	v_pk_fma_f32 v[36:37], v[126:127], v[72:73], v[36:37] op_sel_hi:[1,0,1]
	s_waitcnt vmcnt(16)
	v_pk_fma_f32 v[26:27], v[128:129], v[56:57], v[26:27] op_sel:[0,1,0]
	v_pk_fma_f32 v[28:29], v[130:131], v[56:57], v[28:29] op_sel:[0,1,0]
	v_pk_fma_f32 v[30:31], v[128:129], v[64:65], v[30:31] op_sel:[0,1,0]
	v_pk_fma_f32 v[32:33], v[130:131], v[64:65], v[32:33] op_sel:[0,1,0]
	v_pk_fma_f32 v[34:35], v[128:129], v[72:73], v[34:35] op_sel:[0,1,0]
	v_pk_fma_f32 v[36:37], v[130:131], v[72:73], v[36:37] op_sel:[0,1,0]
	ds_read_b128 v[50:53], v46 offset:224
	ds_read_b128 v[54:57], v46 offset:240
	ds_read_b128 v[58:61], v46 offset:4320
	ds_read_b128 v[62:65], v46 offset:4336
	ds_read_b128 v[66:69], v46 offset:8416
	ds_read_b128 v[70:73], v46 offset:8432
	s_waitcnt lgkmcnt(6)
	s_waitcnt vmcnt(15)
	v_pk_fma_f32 v[26:27], v[132:133], v[2:3], v[26:27] op_sel_hi:[1,0,1]
	v_pk_fma_f32 v[28:29], v[134:135], v[2:3], v[28:29] op_sel_hi:[1,0,1]
	v_pk_fma_f32 v[30:31], v[132:133], v[10:11], v[30:31] op_sel_hi:[1,0,1]
	v_pk_fma_f32 v[32:33], v[134:135], v[10:11], v[32:33] op_sel_hi:[1,0,1]
	v_pk_fma_f32 v[34:35], v[132:133], v[18:19], v[34:35] op_sel_hi:[1,0,1]
	v_pk_fma_f32 v[36:37], v[134:135], v[18:19], v[36:37] op_sel_hi:[1,0,1]
	s_waitcnt vmcnt(14)
	v_pk_fma_f32 v[26:27], v[136:137], v[2:3], v[26:27] op_sel:[0,1,0]
	v_pk_fma_f32 v[28:29], v[138:139], v[2:3], v[28:29] op_sel:[0,1,0]
	v_pk_fma_f32 v[30:31], v[136:137], v[10:11], v[30:31] op_sel:[0,1,0]
	v_pk_fma_f32 v[32:33], v[138:139], v[10:11], v[32:33] op_sel:[0,1,0]
	v_pk_fma_f32 v[34:35], v[136:137], v[18:19], v[34:35] op_sel:[0,1,0]
	v_pk_fma_f32 v[36:37], v[138:139], v[18:19], v[36:37] op_sel:[0,1,0]
	s_waitcnt vmcnt(13)
	v_pk_fma_f32 v[26:27], v[140:141], v[4:5], v[26:27] op_sel_hi:[1,0,1]
	v_pk_fma_f32 v[28:29], v[142:143], v[4:5], v[28:29] op_sel_hi:[1,0,1]
	v_pk_fma_f32 v[30:31], v[140:141], v[12:13], v[30:31] op_sel_hi:[1,0,1]
	v_pk_fma_f32 v[32:33], v[142:143], v[12:13], v[32:33] op_sel_hi:[1,0,1]
	v_pk_fma_f32 v[34:35], v[140:141], v[20:21], v[34:35] op_sel_hi:[1,0,1]
	v_pk_fma_f32 v[36:37], v[142:143], v[20:21], v[36:37] op_sel_hi:[1,0,1]
	s_waitcnt vmcnt(12)
	v_pk_fma_f32 v[26:27], v[144:145], v[4:5], v[26:27] op_sel:[0,1,0]
	v_pk_fma_f32 v[28:29], v[146:147], v[4:5], v[28:29] op_sel:[0,1,0]
	v_pk_fma_f32 v[30:31], v[144:145], v[12:13], v[30:31] op_sel:[0,1,0]
	v_pk_fma_f32 v[32:33], v[146:147], v[12:13], v[32:33] op_sel:[0,1,0]
	v_pk_fma_f32 v[34:35], v[144:145], v[20:21], v[34:35] op_sel:[0,1,0]
	v_pk_fma_f32 v[36:37], v[146:147], v[20:21], v[36:37] op_sel:[0,1,0]
	s_waitcnt vmcnt(11)
	v_pk_fma_f32 v[26:27], v[148:149], v[6:7], v[26:27] op_sel_hi:[1,0,1]
	v_pk_fma_f32 v[28:29], v[150:151], v[6:7], v[28:29] op_sel_hi:[1,0,1]
	v_pk_fma_f32 v[30:31], v[148:149], v[14:15], v[30:31] op_sel_hi:[1,0,1]
	v_pk_fma_f32 v[32:33], v[150:151], v[14:15], v[32:33] op_sel_hi:[1,0,1]
	v_pk_fma_f32 v[34:35], v[148:149], v[22:23], v[34:35] op_sel_hi:[1,0,1]
	v_pk_fma_f32 v[36:37], v[150:151], v[22:23], v[36:37] op_sel_hi:[1,0,1]
	s_waitcnt vmcnt(10)
	v_pk_fma_f32 v[26:27], v[152:153], v[6:7], v[26:27] op_sel:[0,1,0]
	v_pk_fma_f32 v[28:29], v[154:155], v[6:7], v[28:29] op_sel:[0,1,0]
	v_pk_fma_f32 v[30:31], v[152:153], v[14:15], v[30:31] op_sel:[0,1,0]
	v_pk_fma_f32 v[32:33], v[154:155], v[14:15], v[32:33] op_sel:[0,1,0]
	v_pk_fma_f32 v[34:35], v[152:153], v[22:23], v[34:35] op_sel:[0,1,0]
	v_pk_fma_f32 v[36:37], v[154:155], v[22:23], v[36:37] op_sel:[0,1,0]
	s_waitcnt vmcnt(9)
	v_pk_fma_f32 v[26:27], v[156:157], v[8:9], v[26:27] op_sel_hi:[1,0,1]
	v_pk_fma_f32 v[28:29], v[158:159], v[8:9], v[28:29] op_sel_hi:[1,0,1]
	v_pk_fma_f32 v[30:31], v[156:157], v[16:17], v[30:31] op_sel_hi:[1,0,1]
	v_pk_fma_f32 v[32:33], v[158:159], v[16:17], v[32:33] op_sel_hi:[1,0,1]
	v_pk_fma_f32 v[34:35], v[156:157], v[24:25], v[34:35] op_sel_hi:[1,0,1]
	v_pk_fma_f32 v[36:37], v[158:159], v[24:25], v[36:37] op_sel_hi:[1,0,1]
	s_waitcnt vmcnt(8)
	v_pk_fma_f32 v[26:27], v[160:161], v[8:9], v[26:27] op_sel:[0,1,0]
	v_pk_fma_f32 v[28:29], v[162:163], v[8:9], v[28:29] op_sel:[0,1,0]
	v_pk_fma_f32 v[30:31], v[160:161], v[16:17], v[30:31] op_sel:[0,1,0]
	v_pk_fma_f32 v[32:33], v[162:163], v[16:17], v[32:33] op_sel:[0,1,0]
	v_pk_fma_f32 v[34:35], v[160:161], v[24:25], v[34:35] op_sel:[0,1,0]
	v_pk_fma_f32 v[36:37], v[162:163], v[24:25], v[36:37] op_sel:[0,1,0]
	s_waitcnt lgkmcnt(0)
	s_waitcnt vmcnt(7)
	v_pk_fma_f32 v[26:27], v[164:165], v[50:51], v[26:27] op_sel_hi:[1,0,1]
	v_pk_fma_f32 v[28:29], v[166:167], v[50:51], v[28:29] op_sel_hi:[1,0,1]
	v_pk_fma_f32 v[30:31], v[164:165], v[58:59], v[30:31] op_sel_hi:[1,0,1]
	v_pk_fma_f32 v[32:33], v[166:167], v[58:59], v[32:33] op_sel_hi:[1,0,1]
	v_pk_fma_f32 v[34:35], v[164:165], v[66:67], v[34:35] op_sel_hi:[1,0,1]
	v_pk_fma_f32 v[36:37], v[166:167], v[66:67], v[36:37] op_sel_hi:[1,0,1]
	s_waitcnt vmcnt(6)
	v_pk_fma_f32 v[26:27], v[168:169], v[50:51], v[26:27] op_sel:[0,1,0]
	v_pk_fma_f32 v[28:29], v[170:171], v[50:51], v[28:29] op_sel:[0,1,0]
	v_pk_fma_f32 v[30:31], v[168:169], v[58:59], v[30:31] op_sel:[0,1,0]
	v_pk_fma_f32 v[32:33], v[170:171], v[58:59], v[32:33] op_sel:[0,1,0]
	v_pk_fma_f32 v[34:35], v[168:169], v[66:67], v[34:35] op_sel:[0,1,0]
	v_pk_fma_f32 v[36:37], v[170:171], v[66:67], v[36:37] op_sel:[0,1,0]
	s_waitcnt vmcnt(5)
	v_pk_fma_f32 v[26:27], v[172:173], v[52:53], v[26:27] op_sel_hi:[1,0,1]
	v_pk_fma_f32 v[28:29], v[174:175], v[52:53], v[28:29] op_sel_hi:[1,0,1]
	v_pk_fma_f32 v[30:31], v[172:173], v[60:61], v[30:31] op_sel_hi:[1,0,1]
	v_pk_fma_f32 v[32:33], v[174:175], v[60:61], v[32:33] op_sel_hi:[1,0,1]
	v_pk_fma_f32 v[34:35], v[172:173], v[68:69], v[34:35] op_sel_hi:[1,0,1]
	v_pk_fma_f32 v[36:37], v[174:175], v[68:69], v[36:37] op_sel_hi:[1,0,1]
	s_waitcnt vmcnt(4)
	v_pk_fma_f32 v[26:27], v[176:177], v[52:53], v[26:27] op_sel:[0,1,0]
	v_pk_fma_f32 v[28:29], v[178:179], v[52:53], v[28:29] op_sel:[0,1,0]
	v_pk_fma_f32 v[30:31], v[176:177], v[60:61], v[30:31] op_sel:[0,1,0]
	v_pk_fma_f32 v[32:33], v[178:179], v[60:61], v[32:33] op_sel:[0,1,0]
	v_pk_fma_f32 v[34:35], v[176:177], v[68:69], v[34:35] op_sel:[0,1,0]
	v_pk_fma_f32 v[36:37], v[178:179], v[68:69], v[36:37] op_sel:[0,1,0]
	s_waitcnt vmcnt(3)
	v_pk_fma_f32 v[26:27], v[100:101], v[54:55], v[26:27] op_sel_hi:[1,0,1]
	v_pk_fma_f32 v[28:29], v[102:103], v[54:55], v[28:29] op_sel_hi:[1,0,1]
	v_pk_fma_f32 v[30:31], v[100:101], v[62:63], v[30:31] op_sel_hi:[1,0,1]
	v_pk_fma_f32 v[32:33], v[102:103], v[62:63], v[32:33] op_sel_hi:[1,0,1]
	v_pk_fma_f32 v[34:35], v[100:101], v[70:71], v[34:35] op_sel_hi:[1,0,1]
	v_pk_fma_f32 v[36:37], v[102:103], v[70:71], v[36:37] op_sel_hi:[1,0,1]
	s_waitcnt vmcnt(2)
	v_pk_fma_f32 v[26:27], v[104:105], v[54:55], v[26:27] op_sel:[0,1,0]
	v_pk_fma_f32 v[28:29], v[106:107], v[54:55], v[28:29] op_sel:[0,1,0]
	v_pk_fma_f32 v[30:31], v[104:105], v[62:63], v[30:31] op_sel:[0,1,0]
	v_pk_fma_f32 v[32:33], v[106:107], v[62:63], v[32:33] op_sel:[0,1,0]
	v_pk_fma_f32 v[34:35], v[104:105], v[70:71], v[34:35] op_sel:[0,1,0]
	v_pk_fma_f32 v[36:37], v[106:107], v[70:71], v[36:37] op_sel:[0,1,0]
	s_waitcnt vmcnt(1)
	v_pk_fma_f32 v[26:27], v[108:109], v[56:57], v[26:27] op_sel_hi:[1,0,1]
	v_pk_fma_f32 v[28:29], v[110:111], v[56:57], v[28:29] op_sel_hi:[1,0,1]
	v_pk_fma_f32 v[30:31], v[108:109], v[64:65], v[30:31] op_sel_hi:[1,0,1]
	v_pk_fma_f32 v[32:33], v[110:111], v[64:65], v[32:33] op_sel_hi:[1,0,1]
	v_pk_fma_f32 v[34:35], v[108:109], v[72:73], v[34:35] op_sel_hi:[1,0,1]
	v_pk_fma_f32 v[36:37], v[110:111], v[72:73], v[36:37] op_sel_hi:[1,0,1]
	s_waitcnt vmcnt(0)
	v_pk_fma_f32 v[26:27], v[112:113], v[56:57], v[26:27] op_sel:[0,1,0]
	v_pk_fma_f32 v[28:29], v[114:115], v[56:57], v[28:29] op_sel:[0,1,0]
	v_pk_fma_f32 v[30:31], v[112:113], v[64:65], v[30:31] op_sel:[0,1,0]
	v_pk_fma_f32 v[32:33], v[114:115], v[64:65], v[32:33] op_sel:[0,1,0]
	v_pk_fma_f32 v[34:35], v[112:113], v[72:73], v[34:35] op_sel:[0,1,0]
	v_pk_fma_f32 v[36:37], v[114:115], v[72:73], v[36:37] op_sel:[0,1,0]
	s_nop 0
	s_nop 0
	s_nop 0
	s_nop 0
	s_nop 0
	s_nop 0
	s_nop 0
	s_nop 0
	s_nop 0
	s_nop 0
	s_nop 0
	s_nop 0
	s_nop 0
	ds_write_b128 v40, v[26:29] offset:12288
	ds_write_b128 v40, v[30:33] offset:12800
	ds_write_b128 v40, v[34:37] offset:13312
	s_waitcnt lgkmcnt(0)
	s_barrier
	s_and_saveexec_b64 s[6:7], vcc
	s_cbranch_execz .LBB0_958
	s_load_dwordx2 s[8:9], s[48:49], 0x50
	s_mul_i32 s10, s4, 0x1800
	s_ashr_i32 s11, s10, 31
	s_lshl_b64 s[10:11], s[10:11], 2
	s_waitcnt lgkmcnt(0)
	s_add_u32 s5, s8, s10
	s_addc_u32 s9, s9, s11
	s_add_u32 s8, s5, s0
	s_addc_u32 s9, s9, s1
	global_load_dwordx4 v[2:5], v0, s[8:9]
	ds_read_b128 v[6:9], v41 offset:12288
	ds_read_b128 v[10:13], v41 offset:13824
	ds_read_b128 v[14:17], v41 offset:15360
	ds_read_b128 v[18:21], v41 offset:16896
	ds_read_b128 v[22:25], v41 offset:18432
	ds_read_b128 v[26:29], v41 offset:19968
	ds_read_b128 v[30:33], v41 offset:21504
	ds_read_b128 v[34:37], v41 offset:23040
	ds_read_b128 v[44:47], v41 offset:24576
	ds_read_b128 v[48:51], v41 offset:26112
	ds_read_b128 v[52:55], v41 offset:27648
	ds_read_b128 v[56:59], v41 offset:29184
	s_waitcnt vmcnt(0) lgkmcnt(11)
	v_pk_add_f32 v[60:61], v[4:5], v[8:9]
	v_pk_add_f32 v[62:63], v[2:3], v[6:7]
	s_waitcnt lgkmcnt(10)
	v_pk_add_f32 v[12:13], v[60:61], v[12:13]
	v_pk_add_f32 v[10:11], v[62:63], v[10:11]
	s_waitcnt lgkmcnt(9)
	v_pk_add_f32 v[60:61], v[12:13], v[16:17]
	v_pk_add_f32 v[62:63], v[10:11], v[14:15]
	s_waitcnt lgkmcnt(8)
	v_pk_add_f32 v[20:21], v[60:61], v[20:21]
	v_pk_add_f32 v[18:19], v[62:63], v[18:19]
	s_waitcnt lgkmcnt(7)
	v_pk_add_f32 v[20:21], v[20:21], v[24:25]
	v_pk_add_f32 v[18:19], v[18:19], v[22:23]
	s_waitcnt lgkmcnt(6)
	v_pk_add_f32 v[20:21], v[20:21], v[28:29]
	v_pk_add_f32 v[18:19], v[18:19], v[26:27]
	s_waitcnt lgkmcnt(5)
	v_pk_add_f32 v[20:21], v[20:21], v[32:33]
	v_pk_add_f32 v[18:19], v[18:19], v[30:31]
	ds_read_b128 v[2:5], v41 offset:30720
	ds_read_b128 v[6:9], v41 offset:32256
	ds_read_b128 v[10:13], v41 offset:33792
	ds_read_b128 v[14:17], v41 offset:35328
	s_load_dwordx4 s[8:11], s[48:49], 0x140
	s_waitcnt lgkmcnt(0)
	v_pk_add_f32 v[20:21], v[20:21], v[36:37]
	v_pk_add_f32 v[18:19], v[18:19], v[34:35]
	v_pk_add_f32 v[20:21], v[20:21], v[46:47]
	v_pk_add_f32 v[18:19], v[18:19], v[44:45]
	v_pk_add_f32 v[20:21], v[20:21], v[50:51]
	v_pk_add_f32 v[18:19], v[18:19], v[48:49]
	v_pk_add_f32 v[20:21], v[20:21], v[54:55]
	v_pk_add_f32 v[18:19], v[18:19], v[52:53]
	v_pk_add_f32 v[20:21], v[20:21], v[58:59]
	v_pk_add_f32 v[18:19], v[18:19], v[56:57]
	v_mad_u64_u32 v[60:61], s[4:5], s4, 3, v[38:39]
	v_mov_b64_e32 v[62:63], s[10:11]
	v_pk_add_f32 v[4:5], v[20:21], v[4:5]
	v_pk_add_f32 v[2:3], v[18:19], v[2:3]
	v_mad_i64_i32 v[60:61], s[4:5], v60, s13, v[62:63]
	v_pk_add_f32 v[4:5], v[4:5], v[8:9]
	v_pk_add_f32 v[2:3], v[2:3], v[6:7]
	v_lshl_add_u64 v[60:61], v[60:61], 0, s[0:1]
	v_pk_add_f32 v[4:5], v[4:5], v[12:13]
	v_pk_add_f32 v[2:3], v[2:3], v[10:11]
	v_pk_add_f32 v[4:5], v[4:5], v[16:17]
	v_pk_add_f32 v[2:3], v[2:3], v[14:15]
	v_lshl_add_u64 v[6:7], v[60:61], 0, v[0:1]
	global_store_dwordx4 v[6:7], v[2:5], off
	s_branch .LBB0_958
